# baseline (speedup 1.0000x reference)
; __device__ __forceinline__ u32x4 pack8(f32x4 a, f32x4 b) { u32x4 w; w.x = pk2(a[0], a[1]); w.y = pk2(a[2], a[3]); w.z = pk2(b[0], b[1]); w.w = pk2(b[2], b[3]); return w; }
;     __device__ __forceinline__ void operator()(const f32x4 (&acc)[2][2][4][2], const Unit& un, int wr, int wc, int fr, int fq, int lane) const {
;     ...
;         for (int ai = 0; ai < 2; ++ai)
; #pragma unroll
;             for (int m = 0; m < 4; ++m) {
;                 const int row = un.pm * 256 + ai * 128 + wr * 64 + m * 16 + fr; const float s = rs[ai][m];
; #pragma unroll
;                 for (int bj = 0; bj < 2; ++bj) {
;                     f32x4 a = acc[ai][bj][m][0] * s, b = acc[ai][bj][m][1] * s;
; #pragma unroll
;                     for (int j = 0; j < 4; ++j) { a[j] = fmaxf(a[j], 0.f); a[j] *= a[j]; b[j] = fmaxf(b[j], 0.f); b[j] *= b[j]; }
;                     *(u32x4*)(h + (size_t)row * DFF + c0 + bj * 128) = pack8(a, b);
;                 }
.Lmy_p5_join:
	v_lshl_or_b32 v158, s65, 8, v165
	v_ashrrev_i32_e32 v159, 31, v158
	v_pk_mul_f32 v[124:125], v[124:125], v[152:153] op_sel_hi:[1,0]
	v_or_b32_e32 v132, s30, v163
	v_pk_mul_f32 v[128:129], v[128:129], v[152:153] op_sel_hi:[1,0]
	v_pk_mul_f32 v[126:127], v[126:127], v[152:153] op_sel_hi:[1,0]
	v_pk_mul_f32 v[122:123], v[122:123], v[152:153] op_sel_hi:[1,0]
	v_max_f32_e32 v124, 0, v124
	v_ashrrev_i32_e32 v133, 31, v132
	v_max_f32_e32 v126, 0, v126
	v_max_f32_e32 v122, 0, v122
	v_max_f32_e32 v123, 0, v123
	v_max_f32_e32 v128, 0, v128
	v_mul_f32_e32 v131, v124, v124
	v_max_f32_e32 v124, 0, v129
	v_lshlrev_b64 v[160:161], 14, v[132:133]
	v_mul_f32_e32 v126, v126, v126
	v_mul_f32_e32 v122, v122, v122
	v_max_f32_e32 v127, 0, v127
	v_mul_f32_e32 v123, v123, v123
	v_mul_f32_e32 v128, v128, v128
	v_mul_f32_e32 v129, v124, v124
	v_max_f32_e32 v124, 0, v125
	v_mul_f32_e32 v127, v127, v127
	v_mul_f32_e32 v133, v124, v124
	v_cvt_pk_bf16_f32 v124, v126, v127
	v_cvt_pk_bf16_f32 v125, v128, v129
	v_cvt_pk_bf16_f32 v126, v122, v123
	v_lshl_add_u64 v[128:129], s[2:3], 0, v[160:161]
	v_lshlrev_b64 v[122:123], 1, v[158:159]
	v_pk_mul_f32 v[114:115], v[114:115], v[152:153] op_sel_hi:[1,0]
	v_lshl_add_u64 v[128:129], v[128:129], 0, v[122:123]
	v_pk_mul_f32 v[118:119], v[118:119], v[152:153] op_sel_hi:[1,0]
	v_pk_mul_f32 v[116:117], v[116:117], v[152:153] op_sel_hi:[1,0]
	v_max_f32_e32 v114, 0, v114
	v_cvt_pk_bf16_f32 v127, v131, v133
	global_store_dwordx4 v[128:129], v[124:127], off sc0 sc1
	v_pk_mul_f32 v[120:121], v[120:121], v[152:153] op_sel_hi:[1,0]
	v_max_f32_e32 v115, 0, v115
	v_mul_f32_e32 v124, v114, v114
	v_max_f32_e32 v114, 0, v119
	v_max_f32_e32 v116, 0, v116
	v_max_f32_e32 v118, 0, v118
	v_mul_f32_e32 v114, v114, v114
	v_mul_f32_e32 v119, v115, v115
	v_max_f32_e32 v115, 0, v120
	v_mul_f32_e32 v120, v116, v116
	v_max_f32_e32 v116, 0, v121
	v_max_f32_e32 v117, 0, v117
	v_mul_f32_e32 v118, v118, v118
	v_mul_f32_e32 v115, v115, v115
	v_mul_f32_e32 v116, v116, v116
	v_mul_f32_e32 v117, v117, v117
	v_cvt_pk_bf16_f32 v114, v118, v114
	s_waitcnt lgkmcnt(6)
	v_pk_mul_f32 v[108:109], v[108:109], v[154:155] op_sel_hi:[1,0]
	v_pk_mul_f32 v[106:107], v[106:107], v[154:155] op_sel_hi:[1,0]
	v_cvt_pk_bf16_f32 v115, v115, v116
	v_cvt_pk_bf16_f32 v116, v124, v119
	v_cvt_pk_bf16_f32 v117, v120, v117
	global_store_dwordx4 v[128:129], v[114:117], off offset:256 sc0 sc1
	v_pk_mul_f32 v[112:113], v[112:113], v[154:155] op_sel_hi:[1,0]
	v_pk_mul_f32 v[110:111], v[110:111], v[154:155] op_sel_hi:[1,0]
	v_or_b32_e32 v114, 16, v132
	v_max_f32_e32 v106, 0, v106
	v_max_f32_e32 v107, 0, v107
	v_max_f32_e32 v108, 0, v108
	v_ashrrev_i32_e32 v115, 31, v114
	v_max_f32_e32 v110, 0, v110
	v_mul_f32_e32 v116, v106, v106
	v_max_f32_e32 v106, 0, v111
	v_mul_f32_e32 v111, v107, v107
	v_max_f32_e32 v107, 0, v112
	v_mul_f32_e32 v112, v108, v108
	v_max_f32_e32 v108, 0, v113
	v_lshlrev_b64 v[114:115], 14, v[114:115]
	v_mul_f32_e32 v110, v110, v110
	v_mul_f32_e32 v106, v106, v106
	v_mul_f32_e32 v107, v107, v107
	v_mul_f32_e32 v108, v108, v108
	v_max_f32_e32 v109, 0, v109
	v_cvt_pk_bf16_f32 v106, v110, v106
	v_cvt_pk_bf16_f32 v107, v107, v108
	v_cvt_pk_bf16_f32 v108, v116, v111
	v_lshl_add_u64 v[110:111], s[2:3], 0, v[114:115]
	v_pk_mul_f32 v[98:99], v[98:99], v[154:155] op_sel_hi:[1,0]
	v_mul_f32_e32 v109, v109, v109
	v_lshl_add_u64 v[110:111], v[110:111], 0, v[122:123]
	v_pk_mul_f32 v[102:103], v[102:103], v[154:155] op_sel_hi:[1,0]
	v_pk_mul_f32 v[100:101], v[100:101], v[154:155] op_sel_hi:[1,0]
	v_max_f32_e32 v98, 0, v98
	v_cvt_pk_bf16_f32 v109, v112, v109
	global_store_dwordx4 v[110:111], v[106:109], off sc0 sc1
	v_pk_mul_f32 v[104:105], v[104:105], v[154:155] op_sel_hi:[1,0]
	v_max_f32_e32 v99, 0, v99
	v_mul_f32_e32 v106, v98, v98
	v_max_f32_e32 v98, 0, v103
	v_max_f32_e32 v100, 0, v100
	v_max_f32_e32 v102, 0, v102
	v_mul_f32_e32 v98, v98, v98
	v_mul_f32_e32 v103, v99, v99
	v_max_f32_e32 v99, 0, v104
	v_mul_f32_e32 v104, v100, v100
	v_max_f32_e32 v100, 0, v105
	v_max_f32_e32 v101, 0, v101
	v_mul_f32_e32 v102, v102, v102
	v_mul_f32_e32 v99, v99, v99
	v_mul_f32_e32 v100, v100, v100
	v_mul_f32_e32 v101, v101, v101
	v_cvt_pk_bf16_f32 v98, v102, v98
	s_waitcnt lgkmcnt(5)
	v_pk_mul_f32 v[92:93], v[92:93], v[156:157] op_sel_hi:[1,0]
	v_pk_mul_f32 v[90:91], v[90:91], v[156:157] op_sel_hi:[1,0]
	v_cvt_pk_bf16_f32 v99, v99, v100
	v_cvt_pk_bf16_f32 v100, v106, v103
	v_cvt_pk_bf16_f32 v101, v104, v101
	global_store_dwordx4 v[110:111], v[98:101], off offset:256 sc0 sc1
	v_pk_mul_f32 v[96:97], v[96:97], v[156:157] op_sel_hi:[1,0]
	v_pk_mul_f32 v[94:95], v[94:95], v[156:157] op_sel_hi:[1,0]
	v_or_b32_e32 v98, 32, v132
	v_max_f32_e32 v90, 0, v90
	v_max_f32_e32 v91, 0, v91
	v_max_f32_e32 v92, 0, v92
	v_ashrrev_i32_e32 v99, 31, v98
	v_max_f32_e32 v94, 0, v94
	v_mul_f32_e32 v100, v90, v90
	v_max_f32_e32 v90, 0, v95
	v_mul_f32_e32 v95, v91, v91
	v_max_f32_e32 v91, 0, v96
	v_mul_f32_e32 v96, v92, v92
	v_max_f32_e32 v92, 0, v97
	v_lshlrev_b64 v[98:99], 14, v[98:99]
	v_mul_f32_e32 v94, v94, v94
	v_mul_f32_e32 v90, v90, v90
	v_mul_f32_e32 v91, v91, v91
	v_mul_f32_e32 v92, v92, v92
	v_max_f32_e32 v93, 0, v93
	v_cvt_pk_bf16_f32 v90, v94, v90
	v_cvt_pk_bf16_f32 v91, v91, v92
	v_cvt_pk_bf16_f32 v92, v100, v95
	v_lshl_add_u64 v[94:95], s[2:3], 0, v[98:99]
	v_pk_mul_f32 v[82:83], v[82:83], v[156:157] op_sel_hi:[1,0]
	v_mul_f32_e32 v93, v93, v93
	v_lshl_add_u64 v[94:95], v[94:95], 0, v[122:123]
	v_pk_mul_f32 v[86:87], v[86:87], v[156:157] op_sel_hi:[1,0]
	v_pk_mul_f32 v[84:85], v[84:85], v[156:157] op_sel_hi:[1,0]
	v_max_f32_e32 v82, 0, v82
	v_cvt_pk_bf16_f32 v93, v96, v93
	global_store_dwordx4 v[94:95], v[90:93], off sc0 sc1
	v_pk_mul_f32 v[88:89], v[88:89], v[156:157] op_sel_hi:[1,0]
	v_max_f32_e32 v83, 0, v83
	v_mul_f32_e32 v90, v82, v82
	v_max_f32_e32 v82, 0, v87
	v_max_f32_e32 v84, 0, v84
	v_max_f32_e32 v86, 0, v86
	v_mul_f32_e32 v82, v82, v82
	v_mul_f32_e32 v87, v83, v83
	v_max_f32_e32 v83, 0, v88
	v_mul_f32_e32 v88, v84, v84
	v_max_f32_e32 v84, 0, v89
	v_max_f32_e32 v85, 0, v85
	v_mul_f32_e32 v86, v86, v86
	v_mul_f32_e32 v83, v83, v83
	v_mul_f32_e32 v84, v84, v84
	v_mul_f32_e32 v85, v85, v85
	v_cvt_pk_bf16_f32 v82, v86, v82
	s_waitcnt lgkmcnt(4)
; __device__ __forceinline__ u32x4 pack8(f32x4 a, f32x4 b) { u32x4 w; w.x = pk2(a[0], a[1]); w.y = pk2(a[2], a[3]); w.z = pk2(b[0], b[1]); w.w = pk2(b[2], b[3]); return w; }
;     __device__ __forceinline__ void operator()(const f32x4 (&acc)[2][2][4][2], const Unit& un, int wr, int wc, int fr, int fq, int lane) const {
;     ...
;         for (int ai = 0; ai < 2; ++ai)
; #pragma unroll
;             for (int m = 0; m < 4; ++m) {
;                 const int row = un.pm * 256 + ai * 128 + wr * 64 + m * 16 + fr; const float s = rs[ai][m];
; #pragma unroll
;                 for (int bj = 0; bj < 2; ++bj) {
;                     f32x4 a = acc[ai][bj][m][0] * s, b = acc[ai][bj][m][1] * s;
; #pragma unroll
;                     for (int j = 0; j < 4; ++j) { a[j] = fmaxf(a[j], 0.f); a[j] *= a[j]; b[j] = fmaxf(b[j], 0.f); b[j] *= b[j]; }
;                     *(u32x4*)(h + (size_t)row * DFF + c0 + bj * 128) = pack8(a, b);
	v_pk_mul_f32 v[76:77], v[76:77], v[140:141] op_sel_hi:[1,0]
	v_pk_mul_f32 v[74:75], v[74:75], v[140:141] op_sel_hi:[1,0]
	v_cvt_pk_bf16_f32 v83, v83, v84
	v_cvt_pk_bf16_f32 v84, v90, v87
	v_cvt_pk_bf16_f32 v85, v88, v85
	global_store_dwordx4 v[94:95], v[82:85], off offset:256 sc0 sc1
	v_pk_mul_f32 v[80:81], v[80:81], v[140:141] op_sel_hi:[1,0]
	v_pk_mul_f32 v[78:79], v[78:79], v[140:141] op_sel_hi:[1,0]
	v_or_b32_e32 v82, 48, v132
	v_max_f32_e32 v74, 0, v74
	v_max_f32_e32 v75, 0, v75
	v_max_f32_e32 v76, 0, v76
	v_ashrrev_i32_e32 v83, 31, v82
	v_max_f32_e32 v78, 0, v78
	v_mul_f32_e32 v84, v74, v74
	v_max_f32_e32 v74, 0, v79
	v_mul_f32_e32 v79, v75, v75
	v_max_f32_e32 v75, 0, v80
	v_mul_f32_e32 v80, v76, v76
	v_max_f32_e32 v76, 0, v81
	v_lshlrev_b64 v[82:83], 14, v[82:83]
	v_mul_f32_e32 v78, v78, v78
	v_mul_f32_e32 v74, v74, v74
	v_mul_f32_e32 v75, v75, v75
	v_mul_f32_e32 v76, v76, v76
	v_max_f32_e32 v77, 0, v77
	v_cvt_pk_bf16_f32 v74, v78, v74
	v_cvt_pk_bf16_f32 v75, v75, v76
	v_cvt_pk_bf16_f32 v76, v84, v79
	v_lshl_add_u64 v[78:79], s[2:3], 0, v[82:83]
	v_pk_mul_f32 v[66:67], v[66:67], v[140:141] op_sel_hi:[1,0]
	v_mul_f32_e32 v77, v77, v77
	v_lshl_add_u64 v[78:79], v[78:79], 0, v[122:123]
	v_pk_mul_f32 v[70:71], v[70:71], v[140:141] op_sel_hi:[1,0]
	v_pk_mul_f32 v[68:69], v[68:69], v[140:141] op_sel_hi:[1,0]
	v_max_f32_e32 v66, 0, v66
	v_cvt_pk_bf16_f32 v77, v80, v77
	global_store_dwordx4 v[78:79], v[74:77], off sc0 sc1
	v_pk_mul_f32 v[72:73], v[72:73], v[140:141] op_sel_hi:[1,0]
	v_max_f32_e32 v67, 0, v67
	v_mul_f32_e32 v74, v66, v66
	v_max_f32_e32 v66, 0, v71
	v_max_f32_e32 v68, 0, v68
	v_max_f32_e32 v70, 0, v70
	v_mul_f32_e32 v66, v66, v66
	v_mul_f32_e32 v71, v67, v67
	v_max_f32_e32 v67, 0, v72
	v_mul_f32_e32 v72, v68, v68
	v_max_f32_e32 v68, 0, v73
	v_max_f32_e32 v69, 0, v69
	v_mul_f32_e32 v70, v70, v70
	v_mul_f32_e32 v67, v67, v67
	v_mul_f32_e32 v68, v68, v68
	v_mul_f32_e32 v69, v69, v69
	v_cvt_pk_bf16_f32 v66, v70, v66
	s_waitcnt lgkmcnt(3)
	v_pk_mul_f32 v[60:61], v[60:61], v[138:139] op_sel_hi:[1,0]
	v_pk_mul_f32 v[58:59], v[58:59], v[138:139] op_sel_hi:[1,0]
	v_cvt_pk_bf16_f32 v67, v67, v68
	v_cvt_pk_bf16_f32 v68, v74, v71
	v_cvt_pk_bf16_f32 v69, v72, v69
	global_store_dwordx4 v[78:79], v[66:69], off offset:256 sc0 sc1
	v_pk_mul_f32 v[64:65], v[64:65], v[138:139] op_sel_hi:[1,0]
	v_pk_mul_f32 v[62:63], v[62:63], v[138:139] op_sel_hi:[1,0]
	v_add_u32_e32 v66, 0x80, v132
	v_max_f32_e32 v58, 0, v58
	v_max_f32_e32 v59, 0, v59
	v_max_f32_e32 v60, 0, v60
	v_ashrrev_i32_e32 v67, 31, v66
	v_max_f32_e32 v62, 0, v62
	v_mul_f32_e32 v68, v58, v58
	v_max_f32_e32 v58, 0, v63
	v_mul_f32_e32 v63, v59, v59
	v_max_f32_e32 v59, 0, v64
	v_mul_f32_e32 v64, v60, v60
	v_max_f32_e32 v60, 0, v65
	v_lshlrev_b64 v[66:67], 14, v[66:67]
	v_mul_f32_e32 v62, v62, v62
	v_mul_f32_e32 v58, v58, v58
	v_mul_f32_e32 v59, v59, v59
	v_mul_f32_e32 v60, v60, v60
	v_max_f32_e32 v61, 0, v61
	v_cvt_pk_bf16_f32 v58, v62, v58
	v_cvt_pk_bf16_f32 v59, v59, v60
	v_cvt_pk_bf16_f32 v60, v68, v63
	v_lshl_add_u64 v[62:63], s[2:3], 0, v[66:67]
	v_pk_mul_f32 v[50:51], v[50:51], v[138:139] op_sel_hi:[1,0]
	v_mul_f32_e32 v61, v61, v61
	v_lshl_add_u64 v[62:63], v[62:63], 0, v[122:123]
	v_pk_mul_f32 v[54:55], v[54:55], v[138:139] op_sel_hi:[1,0]
	v_pk_mul_f32 v[52:53], v[52:53], v[138:139] op_sel_hi:[1,0]
	v_max_f32_e32 v50, 0, v50
	v_cvt_pk_bf16_f32 v61, v64, v61
	global_store_dwordx4 v[62:63], v[58:61], off sc0 sc1
	v_pk_mul_f32 v[56:57], v[56:57], v[138:139] op_sel_hi:[1,0]
	v_max_f32_e32 v51, 0, v51
	v_mul_f32_e32 v58, v50, v50
	v_max_f32_e32 v50, 0, v55
	v_max_f32_e32 v52, 0, v52
	v_max_f32_e32 v54, 0, v54
	v_mul_f32_e32 v50, v50, v50
	v_mul_f32_e32 v55, v51, v51
	v_max_f32_e32 v51, 0, v56
	v_mul_f32_e32 v56, v52, v52
	v_max_f32_e32 v52, 0, v57
	v_max_f32_e32 v53, 0, v53
	v_mul_f32_e32 v54, v54, v54
	v_mul_f32_e32 v51, v51, v51
	v_mul_f32_e32 v52, v52, v52
	v_mul_f32_e32 v53, v53, v53
	v_cvt_pk_bf16_f32 v50, v54, v50
	s_waitcnt lgkmcnt(2)
	v_pk_mul_f32 v[44:45], v[44:45], v[136:137] op_sel_hi:[1,0]
	v_pk_mul_f32 v[42:43], v[42:43], v[136:137] op_sel_hi:[1,0]
	v_cvt_pk_bf16_f32 v51, v51, v52
	v_cvt_pk_bf16_f32 v52, v58, v55
	v_cvt_pk_bf16_f32 v53, v56, v53
	global_store_dwordx4 v[62:63], v[50:53], off offset:256 sc0 sc1
	v_pk_mul_f32 v[48:49], v[48:49], v[136:137] op_sel_hi:[1,0]
	v_pk_mul_f32 v[46:47], v[46:47], v[136:137] op_sel_hi:[1,0]
	v_add_u32_e32 v50, 0x90, v132
	v_max_f32_e32 v42, 0, v42
	v_max_f32_e32 v43, 0, v43
	v_max_f32_e32 v44, 0, v44
	v_ashrrev_i32_e32 v51, 31, v50
	v_max_f32_e32 v46, 0, v46
	v_mul_f32_e32 v52, v42, v42
	v_max_f32_e32 v42, 0, v47
	v_mul_f32_e32 v47, v43, v43
	v_max_f32_e32 v43, 0, v48
	v_mul_f32_e32 v48, v44, v44
	v_max_f32_e32 v44, 0, v49
	v_lshlrev_b64 v[50:51], 14, v[50:51]
	v_mul_f32_e32 v46, v46, v46
	v_mul_f32_e32 v42, v42, v42
	v_mul_f32_e32 v43, v43, v43
	v_mul_f32_e32 v44, v44, v44
	v_max_f32_e32 v45, 0, v45
	v_cvt_pk_bf16_f32 v42, v46, v42
	v_cvt_pk_bf16_f32 v43, v43, v44
	v_cvt_pk_bf16_f32 v44, v52, v47
	v_lshl_add_u64 v[46:47], s[2:3], 0, v[50:51]
	v_pk_mul_f32 v[34:35], v[34:35], v[136:137] op_sel_hi:[1,0]
	v_mul_f32_e32 v45, v45, v45
	v_lshl_add_u64 v[46:47], v[46:47], 0, v[122:123]
	v_pk_mul_f32 v[38:39], v[38:39], v[136:137] op_sel_hi:[1,0]
	v_pk_mul_f32 v[36:37], v[36:37], v[136:137] op_sel_hi:[1,0]
	v_max_f32_e32 v34, 0, v34
	v_cvt_pk_bf16_f32 v45, v48, v45
	global_store_dwordx4 v[46:47], v[42:45], off sc0 sc1
	v_pk_mul_f32 v[40:41], v[40:41], v[136:137] op_sel_hi:[1,0]
	v_max_f32_e32 v35, 0, v35
	v_mul_f32_e32 v42, v34, v34
	v_max_f32_e32 v34, 0, v39
	v_max_f32_e32 v36, 0, v36
	v_max_f32_e32 v38, 0, v38
	v_mul_f32_e32 v34, v34, v34
	v_mul_f32_e32 v39, v35, v35
	v_max_f32_e32 v35, 0, v40
	v_mul_f32_e32 v40, v36, v36
	v_max_f32_e32 v36, 0, v41
	v_max_f32_e32 v37, 0, v37
	v_mul_f32_e32 v38, v38, v38
	v_mul_f32_e32 v35, v35, v35
	v_mul_f32_e32 v36, v36, v36
	v_mul_f32_e32 v37, v37, v37
	v_cvt_pk_bf16_f32 v34, v38, v34
	s_waitcnt lgkmcnt(1)
; __device__ __forceinline__ u32x4 pack8(f32x4 a, f32x4 b) { u32x4 w; w.x = pk2(a[0], a[1]); w.y = pk2(a[2], a[3]); w.z = pk2(b[0], b[1]); w.w = pk2(b[2], b[3]); return w; }
; #define PG8_BAR __builtin_amdgcn_s_barrier()
;     __device__ __forceinline__ u32x2 pre(int, int, int) const { return (u32x2){0u, 0u}; }
;     __device__ __forceinline__ u32x2 pre(int, int, int) const { return (u32x2){0u, 0u}; }
; template <class Epi, class Sched, bool HN = false>
; __device__ __forceinline__ void gemm_phase(LAS unsigned char* lds, const Gemm g, const Sched& S, const Epi& E) {
;     ...
;         cur = nxt; cA = nA; cB = nB; ++ui;
;         if constexpr (Epi::MID) E.pre(cur, wr, wid, lane, lds);
;         if (wr == 1) PG8_BAR;
;     __device__ __forceinline__ void operator()(const f32x4 (&acc)[2][2][4][2], const Unit& un, int wr, int wc, int fr, int fq, int lane) const {
;     ...
;         for (int ai = 0; ai < 2; ++ai)
; #pragma unroll
;             for (int m = 0; m < 4; ++m) {
;                 const int row = un.pm * 256 + ai * 128 + wr * 64 + m * 16 + fr; const float s = rs[ai][m];
; #pragma unroll
;                 for (int bj = 0; bj < 2; ++bj) {
;                     f32x4 a = acc[ai][bj][m][0] * s, b = acc[ai][bj][m][1] * s;
; #pragma unroll
;                     for (int j = 0; j < 4; ++j) { a[j] = fmaxf(a[j], 0.f); a[j] *= a[j]; b[j] = fmaxf(b[j], 0.f); b[j] *= b[j]; }
;                     *(u32x4*)(h + (size_t)row * DFF + c0 + bj * 128) = pack8(a, b);
	v_pk_mul_f32 v[28:29], v[28:29], v[134:135] op_sel_hi:[1,0]
	v_pk_mul_f32 v[26:27], v[26:27], v[134:135] op_sel_hi:[1,0]
	v_cvt_pk_bf16_f32 v35, v35, v36
	v_cvt_pk_bf16_f32 v36, v42, v39
	v_cvt_pk_bf16_f32 v37, v40, v37
	global_store_dwordx4 v[46:47], v[34:37], off offset:256 sc0 sc1
	v_pk_mul_f32 v[32:33], v[32:33], v[134:135] op_sel_hi:[1,0]
	v_pk_mul_f32 v[30:31], v[30:31], v[134:135] op_sel_hi:[1,0]
	v_add_u32_e32 v34, 0xa0, v132
	v_max_f32_e32 v26, 0, v26
	v_max_f32_e32 v27, 0, v27
	v_max_f32_e32 v28, 0, v28
	v_ashrrev_i32_e32 v35, 31, v34
	v_max_f32_e32 v30, 0, v30
	v_mul_f32_e32 v36, v26, v26
	v_max_f32_e32 v26, 0, v31
	v_mul_f32_e32 v31, v27, v27
	v_max_f32_e32 v27, 0, v32
	v_mul_f32_e32 v32, v28, v28
	v_max_f32_e32 v28, 0, v33
	v_lshlrev_b64 v[34:35], 14, v[34:35]
	v_mul_f32_e32 v30, v30, v30
	v_mul_f32_e32 v26, v26, v26
	v_mul_f32_e32 v27, v27, v27
	v_mul_f32_e32 v28, v28, v28
	v_max_f32_e32 v29, 0, v29
	v_cvt_pk_bf16_f32 v26, v30, v26
	v_cvt_pk_bf16_f32 v27, v27, v28
	v_cvt_pk_bf16_f32 v28, v36, v31
	v_lshl_add_u64 v[30:31], s[2:3], 0, v[34:35]
	v_pk_mul_f32 v[16:17], v[16:17], v[134:135] op_sel_hi:[1,0]
	v_mul_f32_e32 v29, v29, v29
	v_lshl_add_u64 v[30:31], v[30:31], 0, v[122:123]
	v_pk_mul_f32 v[20:21], v[20:21], v[134:135] op_sel_hi:[1,0]
	v_pk_mul_f32 v[18:19], v[18:19], v[134:135] op_sel_hi:[1,0]
	v_max_f32_e32 v16, 0, v16
	v_cvt_pk_bf16_f32 v29, v32, v29
	global_store_dwordx4 v[30:31], v[26:29], off sc0 sc1
	v_pk_mul_f32 v[22:23], v[22:23], v[134:135] op_sel_hi:[1,0]
	v_max_f32_e32 v17, 0, v17
	v_mul_f32_e32 v26, v16, v16
	v_max_f32_e32 v16, 0, v21
	v_max_f32_e32 v18, 0, v18
	v_max_f32_e32 v20, 0, v20
	v_mul_f32_e32 v16, v16, v16
	v_mul_f32_e32 v21, v17, v17
	v_max_f32_e32 v17, 0, v22
	v_mul_f32_e32 v22, v18, v18
	v_max_f32_e32 v18, 0, v23
	v_max_f32_e32 v19, 0, v19
	v_mul_f32_e32 v20, v20, v20
	v_mul_f32_e32 v17, v17, v17
	v_mul_f32_e32 v18, v18, v18
	v_mul_f32_e32 v19, v19, v19
	v_cvt_pk_bf16_f32 v16, v20, v16
	s_waitcnt lgkmcnt(0)
	v_pk_mul_f32 v[10:11], v[10:11], v[130:131] op_sel_hi:[1,0]
	v_pk_mul_f32 v[8:9], v[8:9], v[130:131] op_sel_hi:[1,0]
	v_cvt_pk_bf16_f32 v17, v17, v18
	v_cvt_pk_bf16_f32 v18, v26, v21
	v_cvt_pk_bf16_f32 v19, v22, v19
	global_store_dwordx4 v[30:31], v[16:19], off offset:256 sc0 sc1
	v_pk_mul_f32 v[14:15], v[14:15], v[130:131] op_sel_hi:[1,0]
	v_pk_mul_f32 v[12:13], v[12:13], v[130:131] op_sel_hi:[1,0]
	v_add_u32_e32 v16, 0xb0, v132
	v_max_f32_e32 v8, 0, v8
	v_max_f32_e32 v9, 0, v9
	v_max_f32_e32 v10, 0, v10
	v_ashrrev_i32_e32 v17, 31, v16
	v_max_f32_e32 v12, 0, v12
	v_mul_f32_e32 v18, v8, v8
	v_max_f32_e32 v8, 0, v13
	v_mul_f32_e32 v13, v9, v9
	v_max_f32_e32 v9, 0, v14
	v_mul_f32_e32 v14, v10, v10
	v_max_f32_e32 v10, 0, v15
	v_lshlrev_b64 v[16:17], 14, v[16:17]
	v_mul_f32_e32 v12, v12, v12
	v_mul_f32_e32 v8, v8, v8
	v_mul_f32_e32 v9, v9, v9
	v_mul_f32_e32 v10, v10, v10
	v_max_f32_e32 v11, 0, v11
	v_cvt_pk_bf16_f32 v8, v12, v8
	v_cvt_pk_bf16_f32 v9, v9, v10
	v_cvt_pk_bf16_f32 v10, v18, v13
	v_lshl_add_u64 v[12:13], s[2:3], 0, v[16:17]
	v_pk_mul_f32 v[2:3], v[2:3], v[130:131] op_sel_hi:[1,0]
	v_pk_mul_f32 v[0:1], v[0:1], v[130:131] op_sel_hi:[1,0]
	v_mul_f32_e32 v11, v11, v11
	v_lshl_add_u64 v[12:13], v[12:13], 0, v[122:123]
	v_pk_mul_f32 v[6:7], v[6:7], v[130:131] op_sel_hi:[1,0]
	v_pk_mul_f32 v[4:5], v[4:5], v[130:131] op_sel_hi:[1,0]
	v_max_f32_e32 v0, 0, v0
	v_max_f32_e32 v1, 0, v1
	v_max_f32_e32 v2, 0, v2
	v_cvt_pk_bf16_f32 v11, v14, v11
	global_store_dwordx4 v[12:13], v[8:11], off sc0 sc1
	v_max_f32_e32 v3, 0, v3
	v_max_f32_e32 v4, 0, v4
	v_mul_f32_e32 v8, v0, v0
	v_max_f32_e32 v0, 0, v5
	v_mul_f32_e32 v5, v1, v1
	v_max_f32_e32 v1, 0, v6
	v_mul_f32_e32 v6, v2, v2
	v_max_f32_e32 v2, 0, v7
	v_mul_f32_e32 v0, v0, v0
	v_mul_f32_e32 v1, v1, v1
	v_mul_f32_e32 v2, v2, v2
	v_mul_f32_e32 v3, v3, v3
	s_mov_b64 s[30:31], -1
	s_andn2_b64 vcc, exec, s[0:1]
	v_mul_f32_e32 v4, v4, v4
	v_cvt_pk_bf16_f32 v0, v4, v0
	v_cvt_pk_bf16_f32 v1, v1, v2
	v_cvt_pk_bf16_f32 v2, v8, v5
	v_cvt_pk_bf16_f32 v3, v6, v3
	global_store_dwordx4 v[12:13], v[0:3], off offset:256 sc0 sc1
	s_cbranch_vccnz .LBB0_1263
	s_andn2_b64 vcc, exec, s[24:25]
	s_cbranch_vccnz .LBB0_1262
	s_barrier
	s_branch .LBB0_1262
